# zpost token loop: 32 ds_bpermute lane-xor exchanges replaced by DPP movs (quad_perm / row_shl+row_shr bank-masked / row_ror:8)
# baseline (speedup 1.0000x reference)
.LBB0_538:
	v_add_co_u32_e32 v40, vcc, 0x9500000, v38
	v_lshl_add_u64 v[70:71], s[12:13], 0, v[34:35]
	s_nop 0
	v_addc_co_u32_e32 v41, vcc, 0, v39, vcc
	v_add_co_u32_e32 v44, vcc, 0x9500000, v70
	s_addk_i32 s10, 0x3f00
	s_nop 0
	v_addc_co_u32_e32 v45, vcc, 0, v71, vcc
	v_add_co_u32_e32 v38, vcc, 0x9501000, v38
	s_bfe_u32 s39, s10, 0x80006
	s_nop 0
	v_addc_co_u32_e32 v39, vcc, 0, v39, vcc
	global_load_dwordx2 v[54:55], v[40:41], off offset:3072
	global_load_dwordx2 v[48:49], v[44:45], off offset:3584
	global_load_dwordx2 v[46:47], v[44:45], off offset:3840
	s_nop 0
	global_load_dwordx2 v[44:45], v[38:39], off
	v_add_co_u32_e32 v38, vcc, 0x9501000, v70
	s_add_i32 s40, s25, s37
	s_nop 0
	v_addc_co_u32_e32 v39, vcc, 0, v71, vcc
	global_load_dwordx2 v[40:41], v[38:39], off offset:512
	s_nop 0
	global_load_dwordx2 v[38:39], v[38:39], off offset:768
	v_mov_b32_e32 v70, s40
	v_mov_b32_e32 v71, s39
	v_cndmask_b32_e64 v70, v70, v71, s[0:1]
	v_lshlrev_b32_e32 v70, 3, v70
	v_mov_b32_e32 v71, v0
	v_lshlrev_b64 v[70:71], 2, v[70:71]
	s_waitcnt vmcnt(11)
	v_lshlrev_b32_e32 v74, 16, v42
	v_and_b32_e32 v75, 0xffff0000, v42
	v_cndmask_b32_e64 v42, 0, 1, s[96:97]
	v_lshl_add_u64 v[72:73], v[2:3], 0, v[70:71]
	v_lshl_add_u64 v[70:71], v[4:5], 0, v[70:71]
	v_lshlrev_b32_e32 v76, 16, v43
	v_cmp_ne_u32_e64 s[10:11], 1, v42
	s_andn2_b64 vcc, exec, s[96:97]
	v_and_b32_e32 v77, 0xffff0000, v43
	s_cbranch_vccnz .LBB0_540
	global_load_dwordx4 v[84:87], v[72:73], off
	global_load_dwordx4 v[88:91], v[70:71], off
	s_nop 1
	v_mov_b32_dpp v42, v74 quad_perm:[2,3,0,1] row_mask:0xf bank_mask:0xf
	s_nop 1
	v_mov_b32_dpp v43, v75 quad_perm:[2,3,0,1] row_mask:0xf bank_mask:0xf
	s_waitcnt lgkmcnt(1)
	v_cndmask_b32_e64 v42, v42, -v42, s[8:9]
	s_waitcnt lgkmcnt(0)
	v_cndmask_b32_e64 v43, v43, -v43, s[8:9]
	s_waitcnt vmcnt(0)
	v_pk_mul_f32 v[42:43], v[88:89], v[42:43]
	s_nop 1
	v_mov_b32_dpp v88, v76 quad_perm:[2,3,0,1] row_mask:0xf bank_mask:0xf
	v_mul_f32_e32 v76, v86, v76
	v_pk_fma_f32 v[74:75], v[84:85], v[74:75], v[42:43]
	s_waitcnt lgkmcnt(0)
	v_cndmask_b32_e64 v86, v88, -v88, s[8:9]
	s_nop 1
	v_mov_b32_dpp v88, v77 quad_perm:[2,3,0,1] row_mask:0xf bank_mask:0xf
	v_mul_f32_e32 v86, v90, v86
	v_mov_b32_e32 v90, v87
	s_waitcnt lgkmcnt(0)
	v_cndmask_b32_e64 v89, v88, -v88, s[8:9]
	v_mov_b32_e32 v88, v77
	v_pk_mul_f32 v[88:89], v[90:91], v[88:89]
	s_nop 0
	v_mov_b32_e32 v77, v88
	v_mov_b32_e32 v87, v89
	v_pk_add_f32 v[76:77], v[76:77], v[86:87]
.LBB0_540:
	v_lshl_add_u64 v[42:43], s[12:13], 0, v[30:31]
	v_pk_mul_f32 v[74:75], v[74:75], s[60:61] op_sel_hi:[1,0]
	v_pk_mul_f32 v[76:77], v[76:77], s[60:61] op_sel_hi:[1,0]
	s_mov_b32 s41, 0x17900000
	v_cvt_pk_bf16_f32 v74, v74, v75
	v_cvt_pk_bf16_f32 v75, v76, v77
	v_add_co_u32_e32 v76, vcc, s41, v42
	s_nop 1
	v_addc_co_u32_e32 v77, vcc, 0, v43, vcc
	global_store_dwordx2 v[76:77], v[74:75], off
	s_waitcnt vmcnt(11)
	v_lshlrev_b32_e32 v74, 16, v68
	v_and_b32_e32 v75, 0xffff0000, v68
	v_lshlrev_b32_e32 v76, 16, v69
	s_and_b64 vcc, exec, s[10:11]
	v_and_b32_e32 v68, 0xffff0000, v69
	s_cbranch_vccnz .LBB0_542
	global_load_dwordx4 v[84:87], v[72:73], off
	s_nop 0
	global_load_dwordx4 v[70:73], v[70:71], off
	s_nop 1
	v_mov_b32_dpp v69, v74 quad_perm:[2,3,0,1] row_mask:0xf bank_mask:0xf
	s_nop 1
	v_mov_b32_dpp v77, v75 quad_perm:[2,3,0,1] row_mask:0xf bank_mask:0xf
	s_waitcnt lgkmcnt(1)
	v_cndmask_b32_e64 v88, v69, -v69, s[8:9]
	s_nop 1
	v_mov_b32_dpp v69, v76 quad_perm:[2,3,0,1] row_mask:0xf bank_mask:0xf
	s_waitcnt lgkmcnt(1)
	v_cndmask_b32_e64 v89, v77, -v77, s[8:9]
	s_waitcnt lgkmcnt(0)
	v_cndmask_b32_e64 v69, v69, -v69, s[8:9]
	s_waitcnt vmcnt(1)
	v_mul_f32_e32 v76, v86, v76
	s_waitcnt vmcnt(0)
	v_mul_f32_e32 v86, v72, v69
	s_nop 1
	v_mov_b32_dpp v69, v68 quad_perm:[2,3,0,1] row_mask:0xf bank_mask:0xf
	v_mov_b32_e32 v72, v87
	v_pk_mul_f32 v[70:71], v[70:71], v[88:89]
	s_waitcnt lgkmcnt(0)
	v_cndmask_b32_e64 v69, v69, -v69, s[8:9]
	v_pk_mul_f32 v[68:69], v[72:73], v[68:69]
	v_pk_fma_f32 v[74:75], v[84:85], v[74:75], v[70:71]
	v_mov_b32_e32 v77, v68
	v_mov_b32_e32 v87, v69
	v_pk_add_f32 v[76:77], v[76:77], v[86:87]
	s_nop 0
	v_mov_b32_e32 v68, v77

.LBB0_546:
	s_waitcnt vmcnt(8)
	v_lshlrev_b32_e32 v60, 16, v56
	v_and_b32_e32 v61, 0xffff0000, v56
	v_lshlrev_b32_e32 v64, 16, v57
	v_and_b32_e32 v65, 0xffff0000, v57
	v_lshlrev_b32_e32 v76, 16, v52
	v_and_b32_e32 v77, 0xffff0000, v52
	v_lshlrev_b32_e32 v84, 16, v53
	v_and_b32_e32 v85, 0xffff0000, v53
	v_lshlrev_b32_e32 v86, 16, v50
	v_and_b32_e32 v87, 0xffff0000, v50
	v_lshlrev_b32_e32 v88, 16, v51
	v_and_b32_e32 v89, 0xffff0000, v51
	global_load_dwordx4 v[50:53], v[6:7], off
	global_load_dwordx4 v[56:59], v[6:7], off offset:1024
	global_load_dwordx4 v[72:75], v[6:7], off offset:2048
	v_pk_mul_f32 v[76:77], v[76:77], v[86:87]
	s_and_b64 vcc, exec, s[10:11]
	s_waitcnt vmcnt(1)
	v_pk_mul_f32 v[56:57], v[76:77], v[56:57]
	s_nop 0
	v_pk_fma_f32 v[50:51], v[66:67], v[50:51], v[56:57]
	v_pk_mul_f32 v[56:57], v[84:85], v[88:89]
	s_waitcnt vmcnt(0)
	v_pk_fma_f32 v[50:51], v[62:63], v[72:73], v[50:51]
	v_pk_mul_f32 v[56:57], v[56:57], v[58:59]
	v_pk_mul_f32 v[50:51], v[50:51], v[60:61]
	v_pk_fma_f32 v[52:53], v[70:71], v[52:53], v[56:57]
	v_lshl_add_u64 v[56:57], s[12:13], 0, v[32:33]
	v_pk_fma_f32 v[52:53], v[68:69], v[74:75], v[52:53]
	v_cvt_pk_bf16_f32 v50, v50, v51
	v_pk_mul_f32 v[52:53], v[52:53], v[64:65]
	s_nop 0
	v_cvt_pk_bf16_f32 v51, v52, v53
	global_store_dwordx2 v[56:57], v[50:51], off
	v_mov_b32_e32 v50, s40
	v_mov_b32_e32 v51, s39
	v_cndmask_b32_e64 v50, v50, v51, s[4:5]
	v_lshlrev_b32_e32 v50, 4, v50
	v_mov_b32_e32 v51, v0
	v_lshlrev_b64 v[50:51], 2, v[50:51]
	v_lshl_add_u64 v[52:53], v[8:9], 0, v[50:51]
	v_lshl_add_u64 v[50:51], v[10:11], 0, v[50:51]
	v_lshlrev_b32_e32 v56, 16, v54
	v_and_b32_e32 v57, 0xffff0000, v54
	v_lshlrev_b32_e32 v54, 16, v55
	v_and_b32_e32 v55, 0xffff0000, v55
	s_cbranch_vccnz .LBB0_548
	global_load_dwordx4 v[58:61], v[52:53], off
	global_load_dwordx4 v[62:65], v[50:51], off
	s_nop 1
	v_mov_b32_dpp v66, v56 row_shl:4 row_mask:0xf bank_mask:0x5
	v_mov_b32_dpp v66, v56 row_shr:4 row_mask:0xf bank_mask:0xa
	s_nop 1
	v_mov_b32_dpp v67, v57 row_shl:4 row_mask:0xf bank_mask:0x5
	v_mov_b32_dpp v67, v57 row_shr:4 row_mask:0xf bank_mask:0xa
	s_waitcnt lgkmcnt(1)
	v_cndmask_b32_e64 v66, v66, -v66, s[0:1]
	s_waitcnt lgkmcnt(0)
	v_cndmask_b32_e64 v67, v67, -v67, s[0:1]
	s_waitcnt vmcnt(0)
	v_pk_mul_f32 v[62:63], v[62:63], v[66:67]
	s_nop 1
	v_mov_b32_dpp v66, v54 row_shl:4 row_mask:0xf bank_mask:0x5
	v_mov_b32_dpp v66, v54 row_shr:4 row_mask:0xf bank_mask:0xa
	v_mul_f32_e32 v54, v60, v54
	v_pk_fma_f32 v[56:57], v[58:59], v[56:57], v[62:63]
	s_waitcnt lgkmcnt(0)
	v_cndmask_b32_e64 v60, v66, -v66, s[0:1]
	v_mul_f32_e32 v60, v64, v60
	s_nop 1
	v_mov_b32_dpp v64, v55 row_shl:4 row_mask:0xf bank_mask:0x5
	v_mov_b32_dpp v64, v55 row_shr:4 row_mask:0xf bank_mask:0xa
	v_mov_b32_e32 v66, v55
	s_waitcnt lgkmcnt(0)
	v_cndmask_b32_e64 v67, v64, -v64, s[0:1]
	v_mov_b32_e32 v64, v61
	v_pk_mul_f32 v[64:65], v[64:65], v[66:67]
	s_nop 0
	v_mov_b32_e32 v55, v64
	v_mov_b32_e32 v61, v65
	v_pk_add_f32 v[54:55], v[54:55], v[60:61]
.LBB0_548:
	v_pk_mul_f32 v[56:57], v[56:57], s[44:45] op_sel_hi:[1,0]
	v_pk_mul_f32 v[54:55], v[54:55], s[44:45] op_sel_hi:[1,0]
	s_mov_b32 s14, 0x1a9c0000
	v_cvt_pk_bf16_f32 v56, v56, v57
	v_cvt_pk_bf16_f32 v57, v54, v55
	v_add_co_u32_e32 v54, vcc, s14, v42
	v_lshlrev_b32_e32 v58, 16, v49
	s_nop 0
	v_addc_co_u32_e32 v55, vcc, 0, v43, vcc
	global_store_dwordx2 v[54:55], v[56:57], off
	v_lshlrev_b32_e32 v54, 16, v48
	v_and_b32_e32 v55, 0xffff0000, v48
	s_and_b64 vcc, exec, s[10:11]
	v_and_b32_e32 v56, 0xffff0000, v49
	s_cbranch_vccnz .LBB0_550
	global_load_dwordx4 v[60:63], v[52:53], off
	global_load_dwordx4 v[64:67], v[50:51], off
	s_nop 1
	v_mov_b32_dpp v57, v58 row_shl:4 row_mask:0xf bank_mask:0x5
	v_mov_b32_dpp v57, v58 row_shr:4 row_mask:0xf bank_mask:0xa
	s_nop 1
	v_mov_b32_dpp v48, v54 row_shl:4 row_mask:0xf bank_mask:0x5
	v_mov_b32_dpp v48, v54 row_shr:4 row_mask:0xf bank_mask:0xa
	s_nop 1
	v_mov_b32_dpp v49, v55 row_shl:4 row_mask:0xf bank_mask:0x5
	v_mov_b32_dpp v49, v55 row_shr:4 row_mask:0xf bank_mask:0xa
	s_waitcnt lgkmcnt(2)
	v_cndmask_b32_e64 v57, v57, -v57, s[0:1]
	s_waitcnt lgkmcnt(1)
	v_cndmask_b32_e64 v48, v48, -v48, s[0:1]
	s_waitcnt lgkmcnt(0)
	v_cndmask_b32_e64 v49, v49, -v49, s[0:1]
	s_waitcnt vmcnt(1)
	v_mul_f32_e32 v58, v62, v58
	s_waitcnt vmcnt(0)
	v_mul_f32_e32 v62, v66, v57
	s_nop 1
	v_mov_b32_dpp v57, v56 row_shl:4 row_mask:0xf bank_mask:0x5
	v_mov_b32_dpp v57, v56 row_shr:4 row_mask:0xf bank_mask:0xa
	v_mov_b32_e32 v66, v63
	v_pk_mul_f32 v[48:49], v[64:65], v[48:49]
	s_waitcnt lgkmcnt(0)
	v_cndmask_b32_e64 v57, v57, -v57, s[0:1]
	v_pk_mul_f32 v[56:57], v[66:67], v[56:57]
	v_pk_fma_f32 v[54:55], v[60:61], v[54:55], v[48:49]
	v_mov_b32_e32 v59, v56
	v_mov_b32_e32 v63, v57
	v_pk_add_f32 v[58:59], v[58:59], v[62:63]
	s_nop 0
	v_mov_b32_e32 v56, v59

.LBB0_552:
	s_or_b64 exec, exec, s[14:15]
	global_load_dwordx4 v[54:57], v[12:13], off
	v_lshlrev_b32_e32 v58, 16, v44
	v_and_b32_e32 v59, 0xffff0000, v44
	v_and_b32_e32 v46, 0xffff0000, v45
	v_lshlrev_b32_e32 v47, 16, v45
	v_pk_mul_f32 v[60:61], v[58:59], v[58:59]
	v_pk_mul_f32 v[44:45], v[46:47], v[46:47]
	v_add_f32_e32 v60, v60, v61
	v_add_f32_e32 v45, v45, v60
	v_add_f32_e32 v44, v44, v45
	s_nop 1
	v_mov_b32_dpp v45, v44 quad_perm:[1,0,3,2] row_mask:0xf bank_mask:0xf
	s_waitcnt lgkmcnt(0)
	v_add_f32_e32 v44, v44, v45
	s_nop 1
	v_mov_b32_dpp v45, v44 quad_perm:[2,3,0,1] row_mask:0xf bank_mask:0xf
	s_waitcnt lgkmcnt(0)
	v_add_f32_e32 v44, v44, v45
	s_nop 1
	v_mov_b32_dpp v45, v44 row_shl:4 row_mask:0xf bank_mask:0x5
	v_mov_b32_dpp v45, v44 row_shr:4 row_mask:0xf bank_mask:0xa
	s_waitcnt lgkmcnt(0)
	v_add_f32_e32 v44, v44, v45
	s_nop 1
	v_mov_b32_dpp v45, v44 row_ror:8 row_mask:0xf bank_mask:0xf
	s_waitcnt lgkmcnt(0)
	v_add_f32_e32 v44, v44, v45
	v_fmamk_f32 v44, v44, 0x3c800000, v228
	v_mul_f32_e32 v45, 0x4f800000, v44
	v_cmp_gt_f32_e32 vcc, s49, v44
	s_nop 1
	v_cndmask_b32_e32 v44, v44, v45, vcc
	v_sqrt_f32_e32 v45, v44
	s_nop 0
	v_add_u32_e32 v60, -1, v45
	v_add_u32_e32 v61, 1, v45
	v_fma_f32 v62, -v60, v45, v44
	v_fma_f32 v63, -v61, v45, v44
	v_cmp_ge_f32_e64 s[14:15], 0, v62
	s_nop 1
	v_cndmask_b32_e64 v45, v45, v60, s[14:15]
	v_cmp_lt_f32_e64 s[14:15], 0, v63
	s_nop 1
	v_cndmask_b32_e64 v45, v45, v61, s[14:15]
	v_mul_f32_e32 v60, 0x37800000, v45
	v_cndmask_b32_e32 v45, v45, v60, vcc
	v_cmp_class_f32_e32 vcc, v44, v229
	s_nop 1
	v_cndmask_b32_e32 v44, v45, v44, vcc
	v_div_scale_f32 v45, s[14:15], v44, v44, 1.0
	v_rcp_f32_e32 v60, v45
	v_div_scale_f32 v61, vcc, 1.0, v44, 1.0
	v_fma_f32 v62, -v45, v60, 1.0
	v_fmac_f32_e32 v60, v62, v60
	v_mul_f32_e32 v62, v61, v60
	v_fma_f32 v63, -v45, v62, v61
	v_fmac_f32_e32 v62, v63, v60
	v_fma_f32 v45, -v45, v62, v61
	v_div_fmas_f32 v45, v45, v60, v62
	v_div_fixup_f32 v44, v45, v44, 1.0
	v_pk_mul_f32 v[58:59], v[44:45], v[58:59] op_sel_hi:[0,1]
	v_pk_mul_f32 v[46:47], v[44:45], v[46:47] op_sel_hi:[0,1]
	s_and_b64 vcc, exec, s[10:11]
	s_waitcnt vmcnt(0)
	v_pk_mul_f32 v[44:45], v[54:55], v[58:59]
	v_pk_mul_f32 v[46:47], v[56:57], v[46:47] op_sel:[0,1] op_sel_hi:[1,0]
	s_cbranch_vccnz .LBB0_554
	global_load_dwordx4 v[54:57], v[52:53], off
	global_load_dwordx4 v[58:61], v[50:51], off
	s_nop 1
	v_mov_b32_dpp v62, v44 row_shl:4 row_mask:0xf bank_mask:0x5
	v_mov_b32_dpp v62, v44 row_shr:4 row_mask:0xf bank_mask:0xa
	s_nop 1
	v_mov_b32_dpp v63, v45 row_shl:4 row_mask:0xf bank_mask:0x5
	v_mov_b32_dpp v63, v45 row_shr:4 row_mask:0xf bank_mask:0xa
	s_waitcnt lgkmcnt(1)
	v_cndmask_b32_e64 v62, v62, -v62, s[0:1]
	s_waitcnt lgkmcnt(0)
	v_cndmask_b32_e64 v63, v63, -v63, s[0:1]
	s_waitcnt vmcnt(0)
	v_pk_mul_f32 v[58:59], v[58:59], v[62:63]
	s_nop 1
	v_mov_b32_dpp v62, v46 row_shl:4 row_mask:0xf bank_mask:0x5
	v_mov_b32_dpp v62, v46 row_shr:4 row_mask:0xf bank_mask:0xa
	v_mul_f32_e32 v46, v46, v56
	v_pk_fma_f32 v[44:45], v[44:45], v[54:55], v[58:59]
	s_waitcnt lgkmcnt(0)
	v_cndmask_b32_e64 v56, v62, -v62, s[0:1]
	v_mul_f32_e32 v56, v60, v56
	s_nop 1
	v_mov_b32_dpp v60, v47 row_shl:4 row_mask:0xf bank_mask:0x5
	v_mov_b32_dpp v60, v47 row_shr:4 row_mask:0xf bank_mask:0xa
	v_mov_b32_e32 v62, v47
	s_waitcnt lgkmcnt(0)
	v_cndmask_b32_e64 v63, v60, -v60, s[0:1]
	v_mov_b32_e32 v60, v57
	v_pk_mul_f32 v[60:61], v[62:63], v[60:61]
	s_nop 0
	v_mov_b32_e32 v47, v60
	v_mov_b32_e32 v57, v61
	v_pk_add_f32 v[46:47], v[46:47], v[56:57]
.LBB0_554:
	v_pk_mul_f32 v[44:45], v[44:45], s[44:45] op_sel_hi:[1,0]
	v_pk_mul_f32 v[46:47], v[46:47], s[44:45] op_sel_hi:[1,0]
	v_add_co_u32_e32 v42, vcc, 0x1ca40000, v42
	v_cvt_pk_bf16_f32 v44, v44, v45
	v_cvt_pk_bf16_f32 v45, v46, v47
	v_addc_co_u32_e32 v43, vcc, 0, v43, vcc
	global_store_dwordx2 v[42:43], v[44:45], off
	global_load_dwordx4 v[42:45], v[14:15], off
	v_lshlrev_b32_e32 v54, 16, v40
	v_and_b32_e32 v55, 0xffff0000, v40
	v_and_b32_e32 v46, 0xffff0000, v41
	v_lshlrev_b32_e32 v47, 16, v41
	v_pk_mul_f32 v[56:57], v[54:55], v[54:55]
	v_pk_mul_f32 v[40:41], v[46:47], v[46:47]
	v_add_f32_e32 v56, v56, v57
	v_add_f32_e32 v41, v41, v56
	v_add_f32_e32 v40, v40, v41
	s_nop 1
	v_mov_b32_dpp v41, v40 quad_perm:[1,0,3,2] row_mask:0xf bank_mask:0xf
	s_waitcnt lgkmcnt(0)
	v_add_f32_e32 v40, v40, v41
	s_nop 1
	v_mov_b32_dpp v41, v40 quad_perm:[2,3,0,1] row_mask:0xf bank_mask:0xf
	s_waitcnt lgkmcnt(0)
	v_add_f32_e32 v40, v40, v41
	s_nop 1
	v_mov_b32_dpp v41, v40 row_shl:4 row_mask:0xf bank_mask:0x5
	v_mov_b32_dpp v41, v40 row_shr:4 row_mask:0xf bank_mask:0xa
	s_waitcnt lgkmcnt(0)
	v_add_f32_e32 v40, v40, v41
	s_nop 1
	v_mov_b32_dpp v41, v40 row_ror:8 row_mask:0xf bank_mask:0xf
	s_waitcnt lgkmcnt(0)
	v_add_f32_e32 v40, v40, v41
	v_fmamk_f32 v40, v40, 0x3c800000, v228
	v_mul_f32_e32 v41, 0x4f800000, v40
	v_cmp_gt_f32_e32 vcc, s49, v40
	s_nop 1
	v_cndmask_b32_e32 v40, v40, v41, vcc
	v_sqrt_f32_e32 v41, v40
	s_nop 0
	v_add_u32_e32 v56, -1, v41
	v_add_u32_e32 v57, 1, v41
	v_fma_f32 v58, -v56, v41, v40
	v_fma_f32 v59, -v57, v41, v40
	v_cmp_ge_f32_e64 s[14:15], 0, v58
	s_nop 1
	v_cndmask_b32_e64 v41, v41, v56, s[14:15]
	v_cmp_lt_f32_e64 s[14:15], 0, v59
	s_nop 1
	v_cndmask_b32_e64 v41, v41, v57, s[14:15]
	v_mul_f32_e32 v56, 0x37800000, v41
	v_cndmask_b32_e32 v41, v41, v56, vcc
	v_cmp_class_f32_e32 vcc, v40, v229
	s_nop 1
	v_cndmask_b32_e32 v40, v41, v40, vcc
	v_div_scale_f32 v41, s[14:15], v40, v40, 1.0
	v_rcp_f32_e32 v56, v41
	v_div_scale_f32 v57, vcc, 1.0, v40, 1.0
	v_fma_f32 v58, -v41, v56, 1.0
	v_fmac_f32_e32 v56, v58, v56
	v_mul_f32_e32 v58, v57, v56
	v_fma_f32 v59, -v41, v58, v57
	v_fmac_f32_e32 v58, v59, v56
	v_fma_f32 v41, -v41, v58, v57
	v_div_fmas_f32 v41, v41, v56, v58
	v_div_fixup_f32 v40, v41, v40, 1.0
	v_pk_mul_f32 v[54:55], v[40:41], v[54:55] op_sel_hi:[0,1]
	v_pk_mul_f32 v[46:47], v[40:41], v[46:47] op_sel_hi:[0,1]
	s_and_b64 vcc, exec, s[10:11]
	s_waitcnt vmcnt(0)
	v_pk_mul_f32 v[40:41], v[42:43], v[54:55]
	v_pk_mul_f32 v[42:43], v[44:45], v[46:47] op_sel:[0,1] op_sel_hi:[1,0]
	s_cbranch_vccnz .LBB0_556
	global_load_dwordx4 v[44:47], v[52:53], off
	s_nop 0
	global_load_dwordx4 v[50:53], v[50:51], off
	s_nop 1
	v_mov_b32_dpp v54, v40 row_shl:4 row_mask:0xf bank_mask:0x5
	v_mov_b32_dpp v54, v40 row_shr:4 row_mask:0xf bank_mask:0xa
	s_nop 1
	v_mov_b32_dpp v55, v41 row_shl:4 row_mask:0xf bank_mask:0x5
	v_mov_b32_dpp v55, v41 row_shr:4 row_mask:0xf bank_mask:0xa
	s_waitcnt lgkmcnt(1)
	v_cndmask_b32_e64 v54, v54, -v54, s[0:1]
	s_waitcnt lgkmcnt(0)
	v_cndmask_b32_e64 v55, v55, -v55, s[0:1]
	s_waitcnt vmcnt(0)
	v_pk_mul_f32 v[50:51], v[50:51], v[54:55]
	s_nop 1
	v_mov_b32_dpp v54, v42 row_shl:4 row_mask:0xf bank_mask:0x5
	v_mov_b32_dpp v54, v42 row_shr:4 row_mask:0xf bank_mask:0xa
	v_mul_f32_e32 v42, v42, v46
	v_pk_fma_f32 v[40:41], v[40:41], v[44:45], v[50:51]
	s_waitcnt lgkmcnt(0)
	v_cndmask_b32_e64 v46, v54, -v54, s[0:1]
	v_mul_f32_e32 v46, v52, v46
	s_nop 1
	v_mov_b32_dpp v52, v43 row_shl:4 row_mask:0xf bank_mask:0x5
	v_mov_b32_dpp v52, v43 row_shr:4 row_mask:0xf bank_mask:0xa
	v_mov_b32_e32 v54, v43
	s_waitcnt lgkmcnt(0)
	v_cndmask_b32_e64 v55, v52, -v52, s[0:1]
	v_mov_b32_e32 v52, v47
	v_pk_mul_f32 v[52:53], v[54:55], v[52:53]
	s_nop 0
	v_mov_b32_e32 v43, v52
	v_mov_b32_e32 v47, v53
	v_pk_add_f32 v[42:43], v[42:43], v[46:47]
